# combo15 + fp8 hidden epilogue: the 16 dead zero-init moves in front of the v_cvt_pk_fp8_f32 pairs removed
# baseline (speedup 1.0000x reference)
; __device__ __forceinline__ unsigned cvt_fp8x4(float a, float b, float c, float d) {
;     a = __builtin_amdgcn_fmed3f(a, -448.f, 448.f); b = __builtin_amdgcn_fmed3f(b, -448.f, 448.f); c = __builtin_amdgcn_fmed3f(c, -448.f, 448.f); d = __builtin_amdgcn_fmed3f(d, -448.f, 448.f);
;     int r = 0; r = __builtin_amdgcn_cvt_pk_fp8_f32(a, b, r, false); r = __builtin_amdgcn_cvt_pk_fp8_f32(c, d, r, true); return (unsigned)r; }
.LBB0_331:
	s_andn2_b64 vcc, exec, s[28:29]
	s_ashr_i32 s27, s26, 31
	s_cbranch_vccnz .LBB0_333
	global_load_dwordx4 v[50:53], v[182:183], off offset:16
	global_load_dwordx4 v[68:71], v[182:183], off
	global_load_dwordx4 v[54:57], v[182:183], off offset:528
	global_load_dwordx4 v[74:77], v[182:183], off offset:512
	global_load_dwordx4 v[58:61], v[180:181], off offset:16
	global_load_dwordx4 v[78:81], v[180:181], off
	global_load_dwordx4 v[62:65], v[180:181], off offset:528
	global_load_dwordx4 v[190:193], v[180:181], off offset:512
	s_add_u32 s14, s31, s26
	s_addc_u32 s15, s30, s27
	s_lshl_b64 s[14:15], s[14:15], 14
	v_readlane_b32 s16, v255, 26
	s_add_u32 s28, s16, s14
	v_readlane_b32 s14, v255, 28
	s_addc_u32 s29, s14, s15
	v_readlane_b32 s14, v255, 30
	s_mov_b32 s16, 0x3fb8aa3b
	s_mov_b32 s20, 0xc0317218
	v_or_b32_e32 v0, s14, v217
	s_mov_b32 s14, 0xbfb8aa3b
	v_add_u32_e32 v0, v0, v184
	v_xor_b32_e32 v0, v0, v185
	v_lshrrev_b32_e32 v185, 1, v185
	v_xor_b32_e32 v0, v0, v185
	s_mov_b32 s22, 0x40317218
	s_waitcnt lgkmcnt(0)
	v_pk_mul_f32 v[82:83], v[138:139], v[172:173] op_sel_hi:[0,1]
	v_pk_mul_f32 v[158:159], v[136:137], v[158:159] op_sel_hi:[0,1]
	v_pk_mul_f32 v[142:143], v[134:135], v[142:143] op_sel_hi:[0,1]
	v_pk_mul_f32 v[114:115], v[132:133], v[114:115] op_sel_hi:[0,1]
	v_pk_mul_f32 v[118:119], v[132:133], v[118:119] op_sel_hi:[0,1]
	v_pk_mul_f32 v[116:117], v[132:133], v[116:117] op_sel_hi:[0,1]
	v_pk_mul_f32 v[98:99], v[138:139], v[98:99] op_sel_hi:[0,1]
	v_pk_mul_f32 v[92:93], v[138:139], v[92:93] op_sel_hi:[0,1]
	v_cvt_f32_i32_e32 v47, v47
	v_cvt_f32_i32_e32 v46, v46
	v_lshl_add_u64 v[66:67], s[28:29], 0, v[0:1]
	v_cvt_f32_i32_e32 v49, v49
	v_cvt_f32_i32_e32 v48, v48
	v_pk_mul_f32 v[46:47], v[136:137], v[46:47] op_sel_hi:[0,1]
	v_cvt_f32_i32_e32 v43, v43
	v_cvt_f32_i32_e32 v42, v42
	v_pk_mul_f32 v[48:49], v[136:137], v[48:49] op_sel_hi:[0,1]
	v_cvt_f32_i32_e32 v45, v45
	v_cvt_f32_i32_e32 v44, v44
	v_pk_mul_f32 v[42:43], v[136:137], v[42:43] op_sel_hi:[0,1]
	v_cvt_f32_i32_e32 v39, v39
	v_cvt_f32_i32_e32 v38, v38
	v_pk_mul_f32 v[44:45], v[136:137], v[44:45] op_sel_hi:[0,1]
	v_cvt_f32_i32_e32 v41, v41
	v_cvt_f32_i32_e32 v40, v40
	v_cvt_f32_i32_e32 v35, v35
	v_cvt_f32_i32_e32 v34, v34
	v_cvt_f32_i32_e32 v37, v37
	v_cvt_f32_i32_e32 v36, v36
	v_cvt_f32_i32_e32 v31, v31
	v_cvt_f32_i32_e32 v30, v30
	v_cvt_f32_i32_e32 v33, v33
	v_cvt_f32_i32_e32 v32, v32
	v_cvt_f32_i32_e32 v27, v27
	v_pk_mul_f32 v[30:31], v[134:135], v[30:31] op_sel_hi:[0,1]
	v_cvt_f32_i32_e32 v26, v26
	v_pk_mul_f32 v[32:33], v[134:135], v[32:33] op_sel_hi:[0,1]
	v_cvt_f32_i32_e32 v29, v29
	v_cvt_f32_i32_e32 v28, v28
	v_pk_mul_f32 v[26:27], v[134:135], v[26:27] op_sel_hi:[0,1]
	v_cvt_f32_i32_e32 v23, v23
	v_cvt_f32_i32_e32 v22, v22
	v_pk_mul_f32 v[28:29], v[134:135], v[28:29] op_sel_hi:[0,1]
	v_cvt_f32_i32_e32 v25, v25
	v_cvt_f32_i32_e32 v24, v24
	v_cvt_f32_i32_e32 v19, v19
	v_cvt_f32_i32_e32 v18, v18
	v_cvt_f32_i32_e32 v21, v21
	v_cvt_f32_i32_e32 v20, v20
	v_cvt_f32_i32_e32 v15, v15
	v_cvt_f32_i32_e32 v14, v14
	v_cvt_f32_i32_e32 v17, v17
	v_cvt_f32_i32_e32 v16, v16
	v_cvt_f32_i32_e32 v11, v11
	v_pk_mul_f32 v[14:15], v[132:133], v[14:15] op_sel_hi:[0,1]
	v_cvt_f32_i32_e32 v10, v10
	v_pk_mul_f32 v[16:17], v[132:133], v[16:17] op_sel_hi:[0,1]
	v_cvt_f32_i32_e32 v13, v13
	s_waitcnt vmcnt(0)
	v_pk_mul_f32 v[96:97], v[68:69], s[14:15] op_sel_hi:[1,0]
	v_pk_mul_f32 v[68:69], v[138:139], v[178:179] op_sel_hi:[0,1]
	v_pk_mul_f32 v[182:183], v[70:71], s[14:15] op_sel_hi:[1,0]
	v_pk_mul_f32 v[70:71], v[138:139], v[174:175] op_sel_hi:[0,1]
	v_pk_mul_f32 v[180:181], v[78:79], s[16:17] op_sel_hi:[1,0]
	v_pk_mul_f32 v[184:185], v[80:81], s[16:17] op_sel_hi:[1,0]
	v_pk_fma_f32 v[68:69], v[68:69], v[180:181], v[96:97] neg_lo:[1,0,0] neg_hi:[1,0,0]
	v_pk_fma_f32 v[70:71], v[70:71], v[184:185], v[182:183] neg_lo:[1,0,0] neg_hi:[1,0,0]
	v_exp_f32_e32 v94, v68
	v_exp_f32_e32 v95, v69
	v_exp_f32_e32 v104, v70
	v_exp_f32_e32 v105, v71
	v_add_f32_e32 v94, 1.0, v94
	v_add_f32_e32 v95, 1.0, v95
	v_rcp_f32_e32 v94, v94
	v_rcp_f32_e32 v95, v95
	v_add_f32_e32 v104, 1.0, v104
	v_add_f32_e32 v105, 1.0, v105
	v_rcp_f32_e32 v104, v104
	v_rcp_f32_e32 v105, v105
	v_pk_mul_f32 v[74:75], v[74:75], s[20:21] op_sel_hi:[1,0]
	v_pk_mul_f32 v[78:79], v[190:191], s[22:23] op_sel_hi:[1,0]
	v_pk_mul_f32 v[80:81], v[138:139], v[176:177] op_sel_hi:[0,1]
	v_pk_mul_f32 v[72:73], v[76:77], s[20:21] op_sel_hi:[1,0]
	v_pk_mul_f32 v[76:77], v[192:193], s[22:23] op_sel_hi:[1,0]
	v_pk_fma_f32 v[80:81], v[80:81], v[78:79], v[74:75] neg_lo:[1,0,0] neg_hi:[1,0,0]
	v_pk_mul_f32 v[68:69], v[68:69], v[94:95]
	v_pk_fma_f32 v[82:83], v[82:83], v[76:77], v[72:73] neg_lo:[1,0,0] neg_hi:[1,0,0]
	v_pk_mul_f32 v[70:71], v[70:71], v[104:105]
	v_pk_mul_f32 v[68:69], v[80:81], v[68:69]
	s_mov_b32 s15, 0xc3e00000
	v_pk_mul_f32 v[70:71], v[82:83], v[70:71]
	v_med3_f32 v68, v68, s15, v209
	v_med3_f32 v69, v69, s15, v209
	v_cvt_pk_fp8_f32 v82, v68, v69
	v_med3_f32 v70, v70, s15, v209
	v_med3_f32 v71, v71, s15, v209
	v_pk_fma_f32 v[142:143], v[142:143], v[76:77], v[72:73] neg_lo:[1,0,0] neg_hi:[1,0,0]
	v_cvt_pk_fp8_f32 v82, v70, v71 op_sel:[0,0,1]
	v_mov_b32_e32 v70, v139
	v_pk_mul_f32 v[68:69], v[70:71], v[168:169] op_sel_hi:[0,1]
	v_pk_fma_f32 v[68:69], v[68:69], v[180:181], v[96:97] neg_lo:[1,0,0] neg_hi:[1,0,0]
	v_pk_mul_f32 v[80:81], v[70:71], v[164:165] op_sel_hi:[0,1]
	v_pk_mul_f32 v[94:95], v[70:71], v[170:171] op_sel_hi:[0,1]
	v_pk_mul_f32 v[104:105], v[70:71], v[166:167] op_sel_hi:[0,1]
	v_exp_f32_e32 v71, v68
	v_pk_fma_f32 v[80:81], v[80:81], v[184:185], v[182:183] neg_lo:[1,0,0] neg_hi:[1,0,0]
; __device__ __forceinline__ unsigned cvt_fp8x4(float a, float b, float c, float d) {
;     a = __builtin_amdgcn_fmed3f(a, -448.f, 448.f); b = __builtin_amdgcn_fmed3f(b, -448.f, 448.f); c = __builtin_amdgcn_fmed3f(c, -448.f, 448.f); d = __builtin_amdgcn_fmed3f(d, -448.f, 448.f);
;     int r = 0; r = __builtin_amdgcn_cvt_pk_fp8_f32(a, b, r, false); r = __builtin_amdgcn_cvt_pk_fp8_f32(c, d, r, true); return (unsigned)r; }
	v_pk_fma_f32 v[94:95], v[94:95], v[78:79], v[74:75] neg_lo:[1,0,0] neg_hi:[1,0,0]
	v_pk_fma_f32 v[104:105], v[104:105], v[76:77], v[72:73] neg_lo:[1,0,0] neg_hi:[1,0,0]
	v_add_f32_e32 v71, 1.0, v71
	v_rcp_f32_e32 v164, v71
	v_exp_f32_e32 v71, v69
	v_pk_fma_f32 v[114:115], v[114:115], v[184:185], v[182:183] neg_lo:[1,0,0] neg_hi:[1,0,0]
	v_pk_fma_f32 v[116:117], v[116:117], v[76:77], v[72:73] neg_lo:[1,0,0] neg_hi:[1,0,0]
	v_pk_fma_f32 v[118:119], v[118:119], v[78:79], v[74:75] neg_lo:[1,0,0] neg_hi:[1,0,0]
	v_add_f32_e32 v71, 1.0, v71
	v_rcp_f32_e32 v165, v71
	v_exp_f32_e32 v71, v80
	v_pk_mul_f32 v[50:51], v[50:51], s[14:15] op_sel_hi:[1,0]
	v_pk_mul_f32 v[52:53], v[52:53], s[14:15] op_sel_hi:[1,0]
	v_pk_mul_f32 v[68:69], v[68:69], v[164:165]
	v_add_f32_e32 v71, 1.0, v71
	v_rcp_f32_e32 v166, v71
	v_exp_f32_e32 v71, v81
	v_pk_mul_f32 v[68:69], v[94:95], v[68:69]
	v_med3_f32 v68, v68, s15, v209
	v_add_f32_e32 v71, 1.0, v71
	v_rcp_f32_e32 v167, v71
	v_med3_f32 v69, v69, s15, v209
	v_cvt_pk_fp8_f32 v94, v68, v69
	v_pk_mul_f32 v[68:69], v[136:137], v[160:161] op_sel_hi:[0,1]
	v_pk_mul_f32 v[80:81], v[80:81], v[166:167]
	v_pk_fma_f32 v[68:69], v[68:69], v[78:79], v[74:75] neg_lo:[1,0,0] neg_hi:[1,0,0]
	v_pk_mul_f32 v[80:81], v[104:105], v[80:81]
	v_pk_mul_f32 v[104:105], v[136:137], v[162:163] op_sel_hi:[0,1]
	v_med3_f32 v71, v80, s15, v209
	v_med3_f32 v80, v81, s15, v209
	v_pk_fma_f32 v[104:105], v[104:105], v[180:181], v[96:97] neg_lo:[1,0,0] neg_hi:[1,0,0]
	v_cvt_pk_fp8_f32 v94, v71, v80 op_sel:[0,0,1]
	v_exp_f32_e32 v71, v104
	v_pk_mul_f32 v[80:81], v[136:137], v[156:157] op_sel_hi:[0,1]
	v_pk_fma_f32 v[156:157], v[158:159], v[184:185], v[182:183] neg_lo:[1,0,0] neg_hi:[1,0,0]
	v_pk_fma_f32 v[80:81], v[80:81], v[76:77], v[72:73] neg_lo:[1,0,0] neg_hi:[1,0,0]
	v_add_f32_e32 v71, 1.0, v71
	v_rcp_f32_e32 v158, v71
	v_exp_f32_e32 v71, v105
	v_cvt_f32_i32_e32 v12, v12
	v_pk_mul_f32 v[10:11], v[132:133], v[10:11] op_sel_hi:[0,1]
	v_add_f32_e32 v71, 1.0, v71
	v_rcp_f32_e32 v159, v71
	v_exp_f32_e32 v71, v156
	v_cvt_f32_i32_e32 v3, v3
	v_cvt_f32_i32_e32 v2, v2
	v_pk_mul_f32 v[104:105], v[104:105], v[158:159]
	v_add_f32_e32 v71, 1.0, v71
	v_rcp_f32_e32 v160, v71
	v_exp_f32_e32 v71, v157
	v_pk_mul_f32 v[68:69], v[68:69], v[104:105]
	v_med3_f32 v68, v68, s15, v209
	v_add_f32_e32 v71, 1.0, v71
	v_rcp_f32_e32 v161, v71
	v_med3_f32 v69, v69, s15, v209
	v_cvt_pk_fp8_f32 v158, v68, v69
	v_pk_mul_f32 v[156:157], v[156:157], v[160:161]
	v_pk_mul_f32 v[12:13], v[132:133], v[12:13] op_sel_hi:[0,1]
	v_pk_mul_f32 v[80:81], v[80:81], v[156:157]
	v_mov_b32_e32 v156, v137
	v_pk_mul_f32 v[68:69], v[156:157], v[154:155] op_sel_hi:[0,1]
	v_med3_f32 v71, v80, s15, v209
	v_med3_f32 v80, v81, s15, v209
	v_pk_fma_f32 v[68:69], v[68:69], v[180:181], v[96:97] neg_lo:[1,0,0] neg_hi:[1,0,0]
	v_cvt_pk_fp8_f32 v158, v71, v80 op_sel:[0,0,1]
	v_exp_f32_e32 v71, v68
	v_pk_mul_f32 v[80:81], v[156:157], v[148:149] op_sel_hi:[0,1]
	v_pk_mul_f32 v[148:149], v[156:157], v[150:151] op_sel_hi:[0,1]
	v_pk_fma_f32 v[80:81], v[80:81], v[184:185], v[182:183] neg_lo:[1,0,0] neg_hi:[1,0,0]
	v_add_f32_e32 v71, 1.0, v71
	v_rcp_f32_e32 v150, v71
	v_exp_f32_e32 v71, v69
	v_pk_mul_f32 v[104:105], v[156:157], v[152:153] op_sel_hi:[0,1]
	v_pk_fma_f32 v[104:105], v[104:105], v[78:79], v[74:75] neg_lo:[1,0,0] neg_hi:[1,0,0]
	v_pk_fma_f32 v[148:149], v[148:149], v[76:77], v[72:73] neg_lo:[1,0,0] neg_hi:[1,0,0]
	v_add_f32_e32 v71, 1.0, v71
	v_rcp_f32_e32 v151, v71
	v_exp_f32_e32 v71, v80
	v_pk_mul_f32 v[38:39], v[156:157], v[38:39] op_sel_hi:[0,1]
	v_pk_mul_f32 v[40:41], v[156:157], v[40:41] op_sel_hi:[0,1]
	v_pk_mul_f32 v[68:69], v[68:69], v[150:151]
	v_add_f32_e32 v71, 1.0, v71
	v_rcp_f32_e32 v152, v71
	v_exp_f32_e32 v71, v81
	v_pk_mul_f32 v[68:69], v[104:105], v[68:69]
	v_pk_mul_f32 v[104:105], v[134:135], v[140:141] op_sel_hi:[0,1]
	v_med3_f32 v68, v68, s15, v209
	v_add_f32_e32 v71, 1.0, v71
	v_rcp_f32_e32 v153, v71
	v_med3_f32 v69, v69, s15, v209
	v_pk_mul_f32 v[140:141], v[134:135], v[144:145] op_sel_hi:[0,1]
	v_pk_fma_f32 v[104:105], v[104:105], v[184:185], v[182:183] neg_lo:[1,0,0] neg_hi:[1,0,0]
	v_pk_mul_f32 v[80:81], v[80:81], v[152:153]
	v_pk_fma_f32 v[140:141], v[140:141], v[78:79], v[74:75] neg_lo:[1,0,0] neg_hi:[1,0,0]
	v_pk_mul_f32 v[80:81], v[148:149], v[80:81]
	v_cvt_pk_fp8_f32 v148, v68, v69
	v_med3_f32 v71, v80, s15, v209
	v_med3_f32 v80, v81, s15, v209
	v_pk_mul_f32 v[34:35], v[156:157], v[34:35] op_sel_hi:[0,1]
	v_cvt_pk_fp8_f32 v148, v71, v80 op_sel:[0,0,1]
	v_pk_mul_f32 v[80:81], v[134:135], v[146:147] op_sel_hi:[0,1]
	v_pk_fma_f32 v[80:81], v[80:81], v[180:181], v[96:97] neg_lo:[1,0,0] neg_hi:[1,0,0]
	v_exp_f32_e32 v71, v80
	v_pk_mul_f32 v[36:37], v[156:157], v[36:37] op_sel_hi:[0,1]
	v_cvt_f32_i32_e32 v5, v5
	v_cvt_f32_i32_e32 v4, v4
	v_add_f32_e32 v71, 1.0, v71
	v_rcp_f32_e32 v144, v71
	v_exp_f32_e32 v71, v81
	v_cvt_f32_i32_e32 v7, v7
	v_cvt_f32_i32_e32 v6, v6
	v_cvt_f32_i32_e32 v9, v9
	v_add_f32_e32 v71, 1.0, v71
	v_rcp_f32_e32 v145, v71
	v_exp_f32_e32 v71, v104
	v_cvt_f32_i32_e32 v8, v8
	s_movk_i32 s14, 0x1000
	v_pk_mul_f32 v[80:81], v[80:81], v[144:145]
	v_add_f32_e32 v71, 1.0, v71
	v_rcp_f32_e32 v146, v71
	v_exp_f32_e32 v71, v105
	v_pk_mul_f32 v[80:81], v[140:141], v[80:81]
	v_add_f32_e32 v71, 1.0, v71
	v_rcp_f32_e32 v147, v71
	v_med3_f32 v71, v80, s15, v209
	v_med3_f32 v80, v81, s15, v209
	v_cvt_pk_fp8_f32 v140, v71, v80
	v_pk_mul_f32 v[104:105], v[104:105], v[146:147]
	v_lshl_add_u64 v[68:69], v[66:67], 0, s[18:19]
	v_pk_mul_f32 v[104:105], v[142:143], v[104:105]
	s_nop 0
	v_med3_f32 v81, v104, s15, v209
	v_med3_f32 v83, v105, s15, v209
	v_mov_b32_e32 v104, v135
; __device__ __forceinline__ unsigned cvt_fp8x4(float a, float b, float c, float d) {
;     a = __builtin_amdgcn_fmed3f(a, -448.f, 448.f); b = __builtin_amdgcn_fmed3f(b, -448.f, 448.f); c = __builtin_amdgcn_fmed3f(c, -448.f, 448.f); d = __builtin_amdgcn_fmed3f(d, -448.f, 448.f);
;     int r = 0; r = __builtin_amdgcn_cvt_pk_fp8_f32(a, b, r, false); r = __builtin_amdgcn_cvt_pk_fp8_f32(c, d, r, true); return (unsigned)r; }
	v_cvt_pk_fp8_f32 v140, v81, v83 op_sel:[0,0,1]
	v_pk_mul_f32 v[80:81], v[104:105], v[128:129] op_sel_hi:[0,1]
	v_pk_fma_f32 v[80:81], v[80:81], v[180:181], v[96:97] neg_lo:[1,0,0] neg_hi:[1,0,0]
	v_pk_mul_f32 v[122:123], v[104:105], v[122:123] op_sel_hi:[0,1]
	v_exp_f32_e32 v71, v80
	v_pk_fma_f32 v[122:123], v[122:123], v[184:185], v[182:183] neg_lo:[1,0,0] neg_hi:[1,0,0]
	v_pk_mul_f32 v[126:127], v[104:105], v[126:127] op_sel_hi:[0,1]
	v_pk_mul_f32 v[124:125], v[104:105], v[124:125] op_sel_hi:[0,1]
	v_add_f32_e32 v71, 1.0, v71
	v_rcp_f32_e32 v128, v71
	v_exp_f32_e32 v71, v81
	v_pk_fma_f32 v[124:125], v[124:125], v[76:77], v[72:73] neg_lo:[1,0,0] neg_hi:[1,0,0]
	v_pk_fma_f32 v[126:127], v[126:127], v[78:79], v[74:75] neg_lo:[1,0,0] neg_hi:[1,0,0]
	v_pk_mul_f32 v[22:23], v[104:105], v[22:23] op_sel_hi:[0,1]
	v_add_f32_e32 v71, 1.0, v71
	v_rcp_f32_e32 v129, v71
	v_exp_f32_e32 v71, v122
	v_pk_mul_f32 v[24:25], v[104:105], v[24:25] op_sel_hi:[0,1]
	v_pk_mul_f32 v[18:19], v[104:105], v[18:19] op_sel_hi:[0,1]
	v_pk_mul_f32 v[80:81], v[80:81], v[128:129]
	v_add_f32_e32 v71, 1.0, v71
	v_rcp_f32_e32 v142, v71
	v_exp_f32_e32 v71, v123
	v_pk_mul_f32 v[80:81], v[126:127], v[80:81]
	v_pk_mul_f32 v[20:21], v[104:105], v[20:21] op_sel_hi:[0,1]
	v_mov_b32_e32 v105, 0
	v_add_f32_e32 v71, 1.0, v71
	v_rcp_f32_e32 v143, v71
	v_med3_f32 v71, v80, s15, v209
	v_med3_f32 v80, v81, s15, v209
	v_pk_mul_f32 v[122:123], v[122:123], v[142:143]
	s_nop 0
	v_pk_mul_f32 v[122:123], v[124:125], v[122:123]
	s_nop 0
	v_med3_f32 v81, v122, s15, v209
	v_cvt_pk_fp8_f32 v122, v71, v80
	v_med3_f32 v83, v123, s15, v209
	v_cvt_pk_fp8_f32 v122, v81, v83 op_sel:[0,0,1]
	v_pk_mul_f32 v[80:81], v[132:133], v[120:121] op_sel_hi:[0,1]
	v_pk_fma_f32 v[80:81], v[80:81], v[180:181], v[96:97] neg_lo:[1,0,0] neg_hi:[1,0,0]
	s_nop 0
	v_exp_f32_e32 v71, v80
	s_nop 0
	v_add_f32_e32 v71, 1.0, v71
	v_rcp_f32_e32 v120, v71
	v_exp_f32_e32 v71, v81
	s_nop 0
	v_add_f32_e32 v71, 1.0, v71
	v_rcp_f32_e32 v121, v71
	v_exp_f32_e32 v71, v114
	v_pk_mul_f32 v[80:81], v[80:81], v[120:121]
	v_add_f32_e32 v71, 1.0, v71
	v_rcp_f32_e32 v124, v71
	v_exp_f32_e32 v71, v115
	v_pk_mul_f32 v[80:81], v[118:119], v[80:81]
	v_add_f32_e32 v71, 1.0, v71
	v_rcp_f32_e32 v125, v71
	v_med3_f32 v71, v80, s15, v209
	v_med3_f32 v80, v81, s15, v209
	v_pk_mul_f32 v[114:115], v[114:115], v[124:125]
	s_nop 0
	v_pk_mul_f32 v[114:115], v[116:117], v[114:115]
	s_nop 0
	v_med3_f32 v81, v114, s15, v209
	v_cvt_pk_fp8_f32 v114, v71, v80
	v_mov_b32_e32 v80, v133
	v_pk_mul_f32 v[112:113], v[80:81], v[112:113] op_sel_hi:[0,1]
	v_pk_fma_f32 v[96:97], v[112:113], v[180:181], v[96:97] neg_lo:[1,0,0] neg_hi:[1,0,0]
	v_pk_mul_f32 v[106:107], v[80:81], v[106:107] op_sel_hi:[0,1]
	v_exp_f32_e32 v71, v96
	v_pk_fma_f32 v[106:107], v[106:107], v[184:185], v[182:183] neg_lo:[1,0,0] neg_hi:[1,0,0]
	v_pk_mul_f32 v[110:111], v[80:81], v[110:111] op_sel_hi:[0,1]
	v_pk_mul_f32 v[108:109], v[80:81], v[108:109] op_sel_hi:[0,1]
	v_add_f32_e32 v71, 1.0, v71
	v_rcp_f32_e32 v112, v71
	v_exp_f32_e32 v71, v97
	v_pk_fma_f32 v[72:73], v[108:109], v[76:77], v[72:73] neg_lo:[1,0,0] neg_hi:[1,0,0]
	v_pk_fma_f32 v[74:75], v[110:111], v[78:79], v[74:75] neg_lo:[1,0,0] neg_hi:[1,0,0]
	v_med3_f32 v83, v115, s15, v209
	v_add_f32_e32 v71, 1.0, v71
	v_rcp_f32_e32 v113, v71
	v_exp_f32_e32 v71, v106
	v_cvt_pk_fp8_f32 v114, v81, v83 op_sel:[0,0,1]
	v_pk_mul_f32 v[78:79], v[96:97], v[112:113]
	v_add_f32_e32 v71, 1.0, v71
	v_rcp_f32_e32 v116, v71
	v_exp_f32_e32 v71, v107
	v_pk_mul_f32 v[74:75], v[74:75], v[78:79]
	v_pk_mul_f32 v[2:3], v[80:81], v[2:3] op_sel_hi:[0,1]
	v_add_f32_e32 v71, 1.0, v71
	v_rcp_f32_e32 v117, v71
	v_med3_f32 v71, v74, s15, v209
	v_med3_f32 v74, v75, s15, v209
	v_pk_mul_f32 v[4:5], v[80:81], v[4:5] op_sel_hi:[0,1]
	v_pk_mul_f32 v[76:77], v[106:107], v[116:117]
	v_pk_mul_f32 v[6:7], v[80:81], v[6:7] op_sel_hi:[0,1]
	v_pk_mul_f32 v[72:73], v[72:73], v[76:77]
	v_pk_mul_f32 v[76:77], v[54:55], s[20:21] op_sel_hi:[1,0]
	v_med3_f32 v75, v72, s15, v209
	v_cvt_pk_fp8_f32 v72, v71, v74
	v_med3_f32 v73, v73, s15, v209
	v_pk_mul_f32 v[54:55], v[58:59], s[16:17] op_sel_hi:[1,0]
	v_pk_mul_f32 v[58:59], v[64:65], s[22:23] op_sel_hi:[1,0]
	v_cvt_pk_fp8_f32 v72, v75, v73 op_sel:[0,0,1]
	v_pk_mul_f32 v[74:75], v[56:57], s[20:21] op_sel_hi:[1,0]
	v_pk_mul_f32 v[56:57], v[60:61], s[16:17] op_sel_hi:[1,0]
	v_pk_mul_f32 v[60:61], v[62:63], s[22:23] op_sel_hi:[1,0]
	v_pk_mul_f32 v[62:63], v[138:139], v[102:103] op_sel_hi:[0,1]
	v_pk_fma_f32 v[62:63], v[62:63], v[54:55], v[50:51] neg_lo:[1,0,0] neg_hi:[1,0,0]
	v_pk_mul_f32 v[64:65], v[138:139], v[100:101] op_sel_hi:[0,1]
	v_exp_f32_e32 v71, v62
	v_pk_fma_f32 v[64:65], v[64:65], v[56:57], v[52:53] neg_lo:[1,0,0] neg_hi:[1,0,0]
	v_pk_fma_f32 v[98:99], v[98:99], v[60:61], v[76:77] neg_lo:[1,0,0] neg_hi:[1,0,0]
	v_pk_fma_f32 v[92:93], v[92:93], v[58:59], v[74:75] neg_lo:[1,0,0] neg_hi:[1,0,0]
	v_add_f32_e32 v71, 1.0, v71
	v_rcp_f32_e32 v78, v71
	v_exp_f32_e32 v71, v63
	v_pk_fma_f32 v[46:47], v[46:47], v[54:55], v[50:51] neg_lo:[1,0,0] neg_hi:[1,0,0]
	v_pk_fma_f32 v[48:49], v[48:49], v[56:57], v[52:53] neg_lo:[1,0,0] neg_hi:[1,0,0]
	v_pk_fma_f32 v[42:43], v[42:43], v[60:61], v[76:77] neg_lo:[1,0,0] neg_hi:[1,0,0]
	v_add_f32_e32 v71, 1.0, v71
	v_rcp_f32_e32 v79, v71
	v_exp_f32_e32 v71, v64
	v_pk_fma_f32 v[44:45], v[44:45], v[58:59], v[74:75] neg_lo:[1,0,0] neg_hi:[1,0,0]
	v_pk_fma_f32 v[38:39], v[38:39], v[54:55], v[50:51] neg_lo:[1,0,0] neg_hi:[1,0,0]
	v_pk_mul_f32 v[62:63], v[62:63], v[78:79]
	v_add_f32_e32 v71, 1.0, v71
	v_rcp_f32_e32 v96, v71
	v_exp_f32_e32 v71, v65
	v_pk_mul_f32 v[62:63], v[98:99], v[62:63]
; __device__ __forceinline__ unsigned cvt_fp8x4(float a, float b, float c, float d) {
;     a = __builtin_amdgcn_fmed3f(a, -448.f, 448.f); b = __builtin_amdgcn_fmed3f(b, -448.f, 448.f); c = __builtin_amdgcn_fmed3f(c, -448.f, 448.f); d = __builtin_amdgcn_fmed3f(d, -448.f, 448.f);
;     int r = 0; r = __builtin_amdgcn_cvt_pk_fp8_f32(a, b, r, false); r = __builtin_amdgcn_cvt_pk_fp8_f32(c, d, r, true); return (unsigned)r; }
	v_pk_fma_f32 v[40:41], v[40:41], v[56:57], v[52:53] neg_lo:[1,0,0] neg_hi:[1,0,0]
	v_med3_f32 v62, v62, s15, v209
	v_add_f32_e32 v71, 1.0, v71
	v_rcp_f32_e32 v97, v71
	v_med3_f32 v63, v63, s15, v209
	v_cvt_pk_fp8_f32 v83, v62, v63
	v_pk_mul_f32 v[62:63], v[70:71], v[90:91] op_sel_hi:[0,1]
	v_pk_mul_f32 v[64:65], v[64:65], v[96:97]
	v_pk_fma_f32 v[62:63], v[62:63], v[54:55], v[50:51] neg_lo:[1,0,0] neg_hi:[1,0,0]
	v_pk_mul_f32 v[64:65], v[92:93], v[64:65]
	v_pk_fma_f32 v[34:35], v[34:35], v[60:61], v[76:77] neg_lo:[1,0,0] neg_hi:[1,0,0]
	v_med3_f32 v64, v64, s15, v209
	v_med3_f32 v65, v65, s15, v209
	v_cvt_pk_fp8_f32 v83, v64, v65 op_sel:[0,0,1]
	v_pk_mul_f32 v[64:65], v[70:71], v[88:89] op_sel_hi:[0,1]
	v_exp_f32_e32 v71, v62
	v_pk_fma_f32 v[64:65], v[64:65], v[56:57], v[52:53] neg_lo:[1,0,0] neg_hi:[1,0,0]
	global_store_dwordx2 v0, v[82:83], s[28:29]
	v_pk_fma_f32 v[36:37], v[36:37], v[58:59], v[74:75] neg_lo:[1,0,0] neg_hi:[1,0,0]
	v_add_f32_e32 v71, 1.0, v71
	v_rcp_f32_e32 v78, v71
	v_exp_f32_e32 v71, v63
	v_pk_fma_f32 v[30:31], v[30:31], v[54:55], v[50:51] neg_lo:[1,0,0] neg_hi:[1,0,0]
	v_pk_fma_f32 v[32:33], v[32:33], v[56:57], v[52:53] neg_lo:[1,0,0] neg_hi:[1,0,0]
	v_pk_fma_f32 v[26:27], v[26:27], v[60:61], v[76:77] neg_lo:[1,0,0] neg_hi:[1,0,0]
	v_add_f32_e32 v71, 1.0, v71
	v_rcp_f32_e32 v79, v71
	v_exp_f32_e32 v71, v64
	v_pk_fma_f32 v[28:29], v[28:29], v[58:59], v[74:75] neg_lo:[1,0,0] neg_hi:[1,0,0]
	v_pk_fma_f32 v[22:23], v[22:23], v[54:55], v[50:51] neg_lo:[1,0,0] neg_hi:[1,0,0]
	v_pk_mul_f32 v[62:63], v[62:63], v[78:79]
	v_add_f32_e32 v71, 1.0, v71
	v_rcp_f32_e32 v82, v71
	v_exp_f32_e32 v71, v65
	v_pk_fma_f32 v[24:25], v[24:25], v[56:57], v[52:53] neg_lo:[1,0,0] neg_hi:[1,0,0]
	v_pk_fma_f32 v[18:19], v[18:19], v[60:61], v[76:77] neg_lo:[1,0,0] neg_hi:[1,0,0]
	v_pk_fma_f32 v[20:21], v[20:21], v[58:59], v[74:75] neg_lo:[1,0,0] neg_hi:[1,0,0]
	v_add_f32_e32 v71, 1.0, v71
	v_pk_mul_f32 v[86:87], v[70:71], v[86:87] op_sel_hi:[0,1]
	v_rcp_f32_e32 v83, v71
	v_pk_mul_f32 v[70:71], v[70:71], v[84:85] op_sel_hi:[0,1]
	v_pk_fma_f32 v[84:85], v[86:87], v[60:61], v[76:77] neg_lo:[1,0,0] neg_hi:[1,0,0]
	v_pk_fma_f32 v[70:71], v[70:71], v[58:59], v[74:75] neg_lo:[1,0,0] neg_hi:[1,0,0]
	v_pk_mul_f32 v[62:63], v[84:85], v[62:63]
	v_pk_mul_f32 v[64:65], v[64:65], v[82:83]
	v_med3_f32 v62, v62, s15, v209
	v_med3_f32 v63, v63, s15, v209
	v_cvt_pk_fp8_f32 v95, v62, v63
	v_pk_mul_f32 v[64:65], v[70:71], v[64:65]
	v_pk_fma_f32 v[14:15], v[14:15], v[54:55], v[50:51] neg_lo:[1,0,0] neg_hi:[1,0,0]
	v_med3_f32 v64, v64, s15, v209
	v_med3_f32 v65, v65, s15, v209
	v_cvt_pk_fp8_f32 v95, v64, v65 op_sel:[0,0,1]
	v_pk_fma_f32 v[16:17], v[16:17], v[56:57], v[52:53] neg_lo:[1,0,0] neg_hi:[1,0,0]
	v_pk_fma_f32 v[10:11], v[10:11], v[60:61], v[76:77] neg_lo:[1,0,0] neg_hi:[1,0,0]
	v_pk_fma_f32 v[12:13], v[12:13], v[58:59], v[74:75] neg_lo:[1,0,0] neg_hi:[1,0,0]
	global_store_dwordx2 v0, v[94:95], s[28:29] offset:2048
	v_exp_f32_e32 v0, v46
	v_pk_fma_f32 v[2:3], v[2:3], v[54:55], v[50:51] neg_lo:[1,0,0] neg_hi:[1,0,0]
	v_pk_fma_f32 v[4:5], v[4:5], v[56:57], v[52:53] neg_lo:[1,0,0] neg_hi:[1,0,0]
	v_pk_fma_f32 v[6:7], v[6:7], v[60:61], v[76:77] neg_lo:[1,0,0] neg_hi:[1,0,0]
	v_add_f32_e32 v0, 1.0, v0
	v_rcp_f32_e32 v62, v0
	v_exp_f32_e32 v0, v47
	v_pk_mul_f32 v[8:9], v[80:81], v[8:9] op_sel_hi:[0,1]
	v_pk_fma_f32 v[8:9], v[8:9], v[58:59], v[74:75] neg_lo:[1,0,0] neg_hi:[1,0,0]
	v_add_f32_e32 v0, 1.0, v0
	v_rcp_f32_e32 v63, v0
	v_exp_f32_e32 v0, v48
	v_mov_b32_e32 v74, 0
	v_mov_b32_e32 v56, 0
	v_pk_mul_f32 v[46:47], v[46:47], v[62:63]
	v_add_f32_e32 v0, 1.0, v0
	v_rcp_f32_e32 v64, v0
	v_exp_f32_e32 v0, v49
	v_pk_mul_f32 v[42:43], v[42:43], v[46:47]
	v_mov_b32_e32 v54, 0
	v_med3_f32 v42, v42, s15, v209
	v_add_f32_e32 v0, 1.0, v0
	v_rcp_f32_e32 v65, v0
	v_med3_f32 v43, v43, s15, v209
	v_cvt_pk_fp8_f32 v159, v42, v43
	v_add_co_u32_e32 v42, vcc, s14, v66
	v_pk_mul_f32 v[48:49], v[48:49], v[64:65]
	s_nop 0
	v_addc_co_u32_e32 v43, vcc, 0, v67, vcc
	v_pk_mul_f32 v[44:45], v[44:45], v[48:49]
; __device__ __forceinline__ unsigned cvt_fp8x4(float a, float b, float c, float d) {
;     a = __builtin_amdgcn_fmed3f(a, -448.f, 448.f); b = __builtin_amdgcn_fmed3f(b, -448.f, 448.f); c = __builtin_amdgcn_fmed3f(c, -448.f, 448.f); d = __builtin_amdgcn_fmed3f(d, -448.f, 448.f);
;     int r = 0; r = __builtin_amdgcn_cvt_pk_fp8_f32(a, b, r, false); r = __builtin_amdgcn_cvt_pk_fp8_f32(c, d, r, true); return (unsigned)r; }
	v_mov_b32_e32 v64, 0
	v_med3_f32 v0, v44, s15, v209
	v_med3_f32 v44, v45, s15, v209
	v_cvt_pk_fp8_f32 v159, v0, v44 op_sel:[0,0,1]
	v_exp_f32_e32 v0, v38
	v_mov_b32_e32 v82, 0
	v_mov_b32_e32 v78, 0
	global_store_dwordx2 v[42:43], v[158:159], off
	v_add_f32_e32 v0, 1.0, v0
	v_rcp_f32_e32 v44, v0
	v_exp_f32_e32 v0, v39
	s_nop 0
	v_add_f32_e32 v0, 1.0, v0
	v_rcp_f32_e32 v45, v0
	v_exp_f32_e32 v0, v40
	v_pk_mul_f32 v[38:39], v[38:39], v[44:45]
	v_add_f32_e32 v0, 1.0, v0
	v_rcp_f32_e32 v46, v0
	v_exp_f32_e32 v0, v41
	v_pk_mul_f32 v[34:35], v[34:35], v[38:39]
	v_add_f32_e32 v0, 1.0, v0
	v_rcp_f32_e32 v47, v0
	v_med3_f32 v34, v34, s15, v209
	v_med3_f32 v35, v35, s15, v209
	v_cvt_pk_fp8_f32 v149, v34, v35
	v_pk_mul_f32 v[40:41], v[40:41], v[46:47]
	s_nop 0
	v_pk_mul_f32 v[36:37], v[36:37], v[40:41]
	s_nop 0
	v_med3_f32 v0, v36, s15, v209
	v_med3_f32 v36, v37, s15, v209
	v_cvt_pk_fp8_f32 v149, v0, v36 op_sel:[0,0,1]
	v_exp_f32_e32 v0, v30
	global_store_dwordx2 v[42:43], v[148:149], off offset:2048
	v_add_f32_e32 v0, 1.0, v0
	v_rcp_f32_e32 v34, v0
	v_exp_f32_e32 v0, v31
	s_nop 0
	v_add_f32_e32 v0, 1.0, v0
	v_rcp_f32_e32 v35, v0
	v_exp_f32_e32 v0, v32
	v_pk_mul_f32 v[30:31], v[30:31], v[34:35]
	v_add_f32_e32 v0, 1.0, v0
	v_rcp_f32_e32 v36, v0
	v_exp_f32_e32 v0, v33
	v_pk_mul_f32 v[26:27], v[26:27], v[30:31]
	v_add_f32_e32 v0, 1.0, v0
	v_rcp_f32_e32 v37, v0
	v_med3_f32 v26, v26, s15, v209
	v_med3_f32 v27, v27, s15, v209
	v_cvt_pk_fp8_f32 v141, v26, v27
	v_pk_mul_f32 v[32:33], v[32:33], v[36:37]
	s_nop 0
	v_pk_mul_f32 v[28:29], v[28:29], v[32:33]
	s_nop 0
	v_med3_f32 v0, v28, s15, v209
	v_med3_f32 v28, v29, s15, v209
	v_cvt_pk_fp8_f32 v141, v0, v28 op_sel:[0,0,1]
	v_exp_f32_e32 v0, v22
	global_store_dwordx2 v[68:69], v[140:141], off
	v_add_f32_e32 v0, 1.0, v0
	v_rcp_f32_e32 v26, v0
	v_exp_f32_e32 v0, v23
	s_nop 0
	v_add_f32_e32 v0, 1.0, v0
	v_rcp_f32_e32 v27, v0
	v_exp_f32_e32 v0, v24
	v_pk_mul_f32 v[22:23], v[22:23], v[26:27]
	v_add_f32_e32 v0, 1.0, v0
	v_rcp_f32_e32 v28, v0
	v_exp_f32_e32 v0, v25
	v_pk_mul_f32 v[18:19], v[18:19], v[22:23]
	v_add_f32_e32 v0, 1.0, v0
	v_rcp_f32_e32 v29, v0
	v_med3_f32 v18, v18, s15, v209
	v_med3_f32 v19, v19, s15, v209
	v_cvt_pk_fp8_f32 v123, v18, v19
	v_pk_mul_f32 v[24:25], v[24:25], v[28:29]
	s_nop 0
	v_pk_mul_f32 v[20:21], v[20:21], v[24:25]
	s_nop 0
	v_med3_f32 v0, v20, s15, v209
	v_med3_f32 v20, v21, s15, v209
	v_cvt_pk_fp8_f32 v123, v0, v20 op_sel:[0,0,1]
	v_exp_f32_e32 v0, v14
	global_store_dwordx2 v[68:69], v[122:123], off offset:2048
	v_add_f32_e32 v0, 1.0, v0
	v_rcp_f32_e32 v18, v0
	v_exp_f32_e32 v0, v15
	s_nop 0
	v_add_f32_e32 v0, 1.0, v0
	v_rcp_f32_e32 v19, v0
	v_exp_f32_e32 v0, v16
	v_pk_mul_f32 v[14:15], v[14:15], v[18:19]
	v_add_f32_e32 v0, 1.0, v0
	v_rcp_f32_e32 v20, v0
	v_exp_f32_e32 v0, v17
	v_pk_mul_f32 v[10:11], v[10:11], v[14:15]
	v_add_f32_e32 v0, 1.0, v0
	v_rcp_f32_e32 v21, v0
	v_med3_f32 v10, v10, s15, v209
	v_med3_f32 v11, v11, s15, v209
	v_cvt_pk_fp8_f32 v115, v10, v11
	v_pk_mul_f32 v[16:17], v[16:17], v[20:21]
	v_add_co_u32_e32 v10, vcc, s14, v68
	v_pk_mul_f32 v[12:13], v[12:13], v[16:17]
	s_nop 0
	v_addc_co_u32_e32 v11, vcc, 0, v69, vcc
	v_med3_f32 v0, v12, s15, v209
	v_med3_f32 v12, v13, s15, v209
	v_cvt_pk_fp8_f32 v115, v0, v12 op_sel:[0,0,1]
	v_exp_f32_e32 v0, v2
	global_store_dwordx2 v[10:11], v[114:115], off
	v_add_f32_e32 v0, 1.0, v0
	v_rcp_f32_e32 v12, v0
	v_exp_f32_e32 v0, v3
	s_nop 0
	v_add_f32_e32 v0, 1.0, v0
	v_rcp_f32_e32 v13, v0
	v_exp_f32_e32 v0, v4
	v_pk_mul_f32 v[2:3], v[2:3], v[12:13]
	v_add_f32_e32 v0, 1.0, v0
	v_rcp_f32_e32 v14, v0
	v_exp_f32_e32 v0, v5
	v_pk_mul_f32 v[2:3], v[6:7], v[2:3]
	v_add_f32_e32 v0, 1.0, v0
	v_rcp_f32_e32 v15, v0
	v_med3_f32 v2, v2, s15, v209
	v_med3_f32 v3, v3, s15, v209
	v_cvt_pk_fp8_f32 v73, v2, v3
	v_pk_mul_f32 v[4:5], v[4:5], v[14:15]
	s_nop 0
	v_pk_mul_f32 v[4:5], v[8:9], v[4:5]
	s_nop 0
	v_med3_f32 v0, v4, s15, v209
	v_med3_f32 v4, v5, s15, v209
	v_cvt_pk_fp8_f32 v73, v0, v4 op_sel:[0,0,1]
	v_mov_b32_e32 v0, 0
	global_store_dwordx2 v[10:11], v[72:73], off offset:2048
